# k48 + grid barrier attention/conv/decode -> w_out as row-panel rendezvous (12 producer arrivals per panel, all of one batch; the 64 decode-merge WGs wait for the whole grid; decode partials stored wri
# speedup vs baseline: 1.0178x; 1.0040x over previous
.LBB0_441:
	s_or_b64 exec, exec, s[4:5]
	v_ashrrev_i32_e32 v4, 7, v188
	v_mul_lo_u32 v1, v4, s28
	v_add_u32_e32 v6, 0, v1
	v_bitop3_b32 v1, v4, 7, -8 bitop3:0xe0
	v_mul_lo_u32 v1, v1, s28
	v_add_u32_e32 v3, 0, v1
	s_waitcnt lgkmcnt(0)
	s_barrier
	v_add_u32_e32 v1, 0x4400, v3
	ds_read_b32 v7, v6
	ds_read_b32 v3, v3 offset:17408
	v_and_b32_e32 v0, 0x7f, v188
	v_lshlrev_b32_e32 v168, 2, v0
	v_cmp_eq_u32_e32 vcc, 0, v0
	v_add_u32_e32 v0, v6, v168
	v_add_u32_e32 v8, v1, v168
	s_lshl_b32 s4, s35, 5
	ds_read_b32 v9, v0 offset:32
	ds_read_b32 v12, v8 offset:32
	s_waitcnt lgkmcnt(2)
	v_max_f32_e32 v0, v3, v3
	v_max_f32_e32 v8, v7, v7
	s_or_b32 s16, s4, s24
	v_and_b32_e32 v2, -8, v4
	v_max_f32_e32 v0, v8, v0
	v_sub_f32_e32 v3, v3, v0
	v_add_u32_e32 v2, s16, v2
	v_sub_f32_e32 v7, v7, v0
	v_exp_f32_e32 v8, v3
	v_ashrrev_i32_e32 v3, 31, v2
	v_and_b32_e32 v5, 7, v4
	v_exp_f32_e32 v7, v7
	v_lshlrev_b64 v[10:11], 3, v[2:3]
	v_or_b32_e32 v10, v10, v5
	v_mov_b64_e32 v[2:3], s[22:23]
	v_mad_u64_u32 v[2:3], s[4:5], v10, s29, v[2:3]
	v_mad_i32_i24 v3, v11, s29, v3
	s_waitcnt lgkmcnt(0)
	v_mul_f32_e32 v12, v12, v8
	v_fmac_f32_e32 v12, v7, v9
	v_lshl_add_u64 v[10:11], v[2:3], 0, v[168:169]
	global_store_dword v[10:11], v12, off offset:16 sc1
	s_and_saveexec_b64 s[4:5], vcc
	s_cbranch_execz .LBB0_443
	ds_read_b32 v1, v1 offset:4
	ds_read_b32 v9, v6 offset:4
	s_waitcnt lgkmcnt(1)
	v_mul_f32_e32 v1, v8, v1
	s_waitcnt lgkmcnt(0)
	v_fmac_f32_e32 v1, v7, v9
	global_store_dwordx2 v[2:3], v[0:1], off sc1
.LBB0_443:
	s_or_b64 exec, exec, s[4:5]
	v_add_u32_e32 v0, 4, v4
	v_and_b32_e32 v2, -8, v0
	v_and_b32_e32 v9, 7, v0
	v_bitop3_b32 v0, v0, 7, -8 bitop3:0xe0
	v_mul_lo_u32 v0, v0, s28
	v_add_u32_e32 v0, 0, v0
	ds_read_b32 v3, v6 offset:2176
	ds_read_b32 v8, v0 offset:17408
	v_add_u32_e32 v7, 0x880, v6
	v_add_u32_e32 v1, 0x4400, v0
	v_add_u32_e32 v0, v7, v168
	v_add_u32_e32 v6, v1, v168
	ds_read_b32 v12, v0 offset:32
	ds_read_b32 v13, v6 offset:32
	s_waitcnt lgkmcnt(2)
	v_max_f32_e32 v0, v8, v8
	v_max_f32_e32 v6, v3, v3
	v_max_f32_e32 v0, v6, v0
	v_sub_f32_e32 v3, v3, v0
	v_exp_f32_e32 v6, v3
	v_sub_f32_e32 v3, v8, v0
	v_add_u32_e32 v2, s16, v2
	v_exp_f32_e32 v8, v3
	v_ashrrev_i32_e32 v3, 31, v2
	v_lshlrev_b64 v[10:11], 3, v[2:3]
	v_or_b32_e32 v9, v10, v9
	v_mov_b64_e32 v[2:3], s[22:23]
	v_mad_u64_u32 v[2:3], s[4:5], v9, s29, v[2:3]
	v_mad_i32_i24 v3, v11, s29, v3
	s_waitcnt lgkmcnt(0)
	v_mul_f32_e32 v9, v13, v8
	v_fmac_f32_e32 v9, v6, v12
	v_lshl_add_u64 v[10:11], v[2:3], 0, v[168:169]
	global_store_dword v[10:11], v9, off offset:16 sc1
	s_and_saveexec_b64 s[4:5], vcc
	s_cbranch_execz .LBB0_445
	ds_read_b32 v1, v1 offset:4
	ds_read_b32 v9, v7 offset:4
	s_waitcnt lgkmcnt(1)
	v_mul_f32_e32 v1, v8, v1
	s_waitcnt lgkmcnt(0)
	v_fmac_f32_e32 v1, v6, v9
	global_store_dwordx2 v[2:3], v[0:1], off sc1
.LBB0_445:
	s_or_b64 exec, exec, s[4:5]
	v_add_u32_e32 v0, 8, v4
	v_and_b32_e32 v2, -8, v0
	v_or_b32_e32 v0, v2, v5
	v_mul_lo_u32 v0, v0, s28
	v_add_u32_e32 v0, 0, v0
	ds_read_b32 v3, v7 offset:2176
	ds_read_b32 v8, v0 offset:17408
	v_add_u32_e32 v6, 0x880, v7
	v_add_u32_e32 v1, 0x4400, v0
	v_add_u32_e32 v0, v6, v168
	v_add_u32_e32 v7, v1, v168
	ds_read_b32 v9, v0 offset:32
	ds_read_b32 v12, v7 offset:32
	s_waitcnt lgkmcnt(2)
	v_max_f32_e32 v0, v8, v8
	v_max_f32_e32 v7, v3, v3
	v_max_f32_e32 v0, v7, v0
	v_sub_f32_e32 v3, v3, v0
	v_exp_f32_e32 v7, v3
	v_sub_f32_e32 v3, v8, v0
	v_add_u32_e32 v2, s16, v2
	v_exp_f32_e32 v8, v3
	v_ashrrev_i32_e32 v3, 31, v2
	v_lshlrev_b64 v[10:11], 3, v[2:3]
	v_or_b32_e32 v10, v10, v5
	v_mov_b64_e32 v[2:3], s[22:23]
	v_mad_u64_u32 v[2:3], s[4:5], v10, s29, v[2:3]
	v_mad_i32_i24 v3, v11, s29, v3
	s_waitcnt lgkmcnt(0)
	v_mul_f32_e32 v12, v12, v8
	v_fmac_f32_e32 v12, v7, v9
	v_lshl_add_u64 v[10:11], v[2:3], 0, v[168:169]
	global_store_dword v[10:11], v12, off offset:16 sc1
	s_and_saveexec_b64 s[4:5], vcc
	s_cbranch_execz .LBB0_447
	ds_read_b32 v1, v1 offset:4
	ds_read_b32 v9, v6 offset:4
	s_waitcnt lgkmcnt(1)
	v_mul_f32_e32 v1, v8, v1
	s_waitcnt lgkmcnt(0)
	v_fmac_f32_e32 v1, v7, v9
	global_store_dwordx2 v[2:3], v[0:1], off sc1
.LBB0_447:
	s_or_b64 exec, exec, s[4:5]
	v_add_u32_e32 v0, 12, v4
	v_and_b32_e32 v2, -8, v0
	v_and_b32_e32 v9, 7, v0
	v_bitop3_b32 v0, v0, 7, -8 bitop3:0xe0
	v_mul_lo_u32 v0, v0, s28
	v_add_u32_e32 v0, 0, v0
	ds_read_b32 v3, v6 offset:2176
	ds_read_b32 v8, v0 offset:17408
	v_add_u32_e32 v7, 0x880, v6
	v_add_u32_e32 v1, 0x4400, v0
	v_add_u32_e32 v0, v7, v168
	v_add_u32_e32 v6, v1, v168
	ds_read_b32 v12, v0 offset:32
	ds_read_b32 v13, v6 offset:32
	s_waitcnt lgkmcnt(2)
	v_max_f32_e32 v0, v8, v8
	v_max_f32_e32 v6, v3, v3
	v_max_f32_e32 v0, v6, v0
	v_sub_f32_e32 v3, v3, v0
	v_exp_f32_e32 v6, v3
	v_sub_f32_e32 v3, v8, v0
	v_add_u32_e32 v2, s16, v2
	v_exp_f32_e32 v8, v3
	v_ashrrev_i32_e32 v3, 31, v2
	v_lshlrev_b64 v[10:11], 3, v[2:3]
	v_or_b32_e32 v9, v10, v9
	v_mov_b64_e32 v[2:3], s[22:23]
	v_mad_u64_u32 v[2:3], s[4:5], v9, s29, v[2:3]
	v_mad_i32_i24 v3, v11, s29, v3
	s_waitcnt lgkmcnt(0)
	v_mul_f32_e32 v9, v13, v8
	v_fmac_f32_e32 v9, v6, v12
	v_lshl_add_u64 v[10:11], v[2:3], 0, v[168:169]
	global_store_dword v[10:11], v9, off offset:16 sc1
	s_and_saveexec_b64 s[4:5], vcc
	s_cbranch_execz .LBB0_449
	ds_read_b32 v1, v1 offset:4
	ds_read_b32 v9, v7 offset:4
	s_waitcnt lgkmcnt(1)
	v_mul_f32_e32 v1, v8, v1
	s_waitcnt lgkmcnt(0)
	v_fmac_f32_e32 v1, v6, v9
	global_store_dwordx2 v[2:3], v[0:1], off sc1
.LBB0_449:
	s_or_b64 exec, exec, s[4:5]
	v_add_u32_e32 v0, 16, v4
	v_and_b32_e32 v2, -8, v0
	v_or_b32_e32 v0, v2, v5
	v_mul_lo_u32 v0, v0, s28
	v_add_u32_e32 v0, 0, v0
	ds_read_b32 v3, v7 offset:2176
	ds_read_b32 v8, v0 offset:17408
	v_add_u32_e32 v6, 0x880, v7
	v_add_u32_e32 v1, 0x4400, v0
	v_add_u32_e32 v0, v6, v168
	v_add_u32_e32 v7, v1, v168
	ds_read_b32 v9, v0 offset:32
	ds_read_b32 v12, v7 offset:32
	s_waitcnt lgkmcnt(2)
	v_max_f32_e32 v0, v8, v8
	v_max_f32_e32 v7, v3, v3
	v_max_f32_e32 v0, v7, v0
	v_sub_f32_e32 v3, v3, v0
	v_exp_f32_e32 v7, v3
	v_sub_f32_e32 v3, v8, v0
	v_add_u32_e32 v2, s16, v2
	v_exp_f32_e32 v8, v3
	v_ashrrev_i32_e32 v3, 31, v2
	v_lshlrev_b64 v[10:11], 3, v[2:3]
	v_or_b32_e32 v10, v10, v5
	v_mov_b64_e32 v[2:3], s[22:23]
	v_mad_u64_u32 v[2:3], s[4:5], v10, s29, v[2:3]
	v_mad_i32_i24 v3, v11, s29, v3
	s_waitcnt lgkmcnt(0)
	v_mul_f32_e32 v12, v12, v8
	v_fmac_f32_e32 v12, v7, v9
	v_lshl_add_u64 v[10:11], v[2:3], 0, v[168:169]
	global_store_dword v[10:11], v12, off offset:16 sc1
	s_and_saveexec_b64 s[4:5], vcc
	s_cbranch_execz .LBB0_451
	ds_read_b32 v1, v1 offset:4
	ds_read_b32 v9, v6 offset:4
	s_waitcnt lgkmcnt(1)
	v_mul_f32_e32 v1, v8, v1
	s_waitcnt lgkmcnt(0)
	v_fmac_f32_e32 v1, v7, v9
	global_store_dwordx2 v[2:3], v[0:1], off sc1
.LBB0_451:
	s_or_b64 exec, exec, s[4:5]
	v_add_u32_e32 v0, 20, v4
	v_and_b32_e32 v2, -8, v0
	v_and_b32_e32 v9, 7, v0
	v_bitop3_b32 v0, v0, 7, -8 bitop3:0xe0
	v_mul_lo_u32 v0, v0, s28
	v_add_u32_e32 v0, 0, v0
	ds_read_b32 v3, v6 offset:2176
	ds_read_b32 v8, v0 offset:17408
	v_add_u32_e32 v7, 0x880, v6
	v_add_u32_e32 v1, 0x4400, v0
	v_add_u32_e32 v0, v7, v168
	v_add_u32_e32 v6, v1, v168
	ds_read_b32 v12, v0 offset:32
	ds_read_b32 v13, v6 offset:32
	s_waitcnt lgkmcnt(2)
	v_max_f32_e32 v0, v8, v8
	v_max_f32_e32 v6, v3, v3
	v_max_f32_e32 v0, v6, v0
	v_sub_f32_e32 v3, v3, v0
	v_exp_f32_e32 v6, v3
	v_sub_f32_e32 v3, v8, v0
	v_add_u32_e32 v2, s16, v2
	v_exp_f32_e32 v8, v3
	v_ashrrev_i32_e32 v3, 31, v2
	v_lshlrev_b64 v[10:11], 3, v[2:3]
	v_or_b32_e32 v9, v10, v9
	v_mov_b64_e32 v[2:3], s[22:23]
	v_mad_u64_u32 v[2:3], s[4:5], v9, s29, v[2:3]
	v_mad_i32_i24 v3, v11, s29, v3
	s_waitcnt lgkmcnt(0)
	v_mul_f32_e32 v9, v13, v8
	v_fmac_f32_e32 v9, v6, v12
	v_lshl_add_u64 v[10:11], v[2:3], 0, v[168:169]
	global_store_dword v[10:11], v9, off offset:16 sc1
	s_and_saveexec_b64 s[4:5], vcc
	s_cbranch_execz .LBB0_453
	ds_read_b32 v1, v1 offset:4
	ds_read_b32 v9, v7 offset:4
	s_waitcnt lgkmcnt(1)
	v_mul_f32_e32 v1, v8, v1
	s_waitcnt lgkmcnt(0)
	v_fmac_f32_e32 v1, v6, v9
	global_store_dwordx2 v[2:3], v[0:1], off sc1
.LBB0_453:
	s_or_b64 exec, exec, s[4:5]
	v_add_u32_e32 v0, 24, v4
	v_and_b32_e32 v2, -8, v0
	v_or_b32_e32 v0, v2, v5
	v_mul_lo_u32 v0, v0, s28
	v_add_u32_e32 v0, 0, v0
	ds_read_b32 v3, v7 offset:2176
	ds_read_b32 v8, v0 offset:17408
	v_add_u32_e32 v6, 0x880, v7
	v_add_u32_e32 v1, 0x4400, v0
	v_add_u32_e32 v0, v6, v168
	v_add_u32_e32 v7, v1, v168
	ds_read_b32 v9, v0 offset:32
	ds_read_b32 v12, v7 offset:32
	s_waitcnt lgkmcnt(2)
	v_max_f32_e32 v0, v8, v8
	v_max_f32_e32 v7, v3, v3
	v_max_f32_e32 v0, v7, v0
	v_sub_f32_e32 v3, v3, v0
	v_exp_f32_e32 v7, v3
	v_sub_f32_e32 v3, v8, v0
	v_add_u32_e32 v2, s16, v2
	v_exp_f32_e32 v8, v3
	v_ashrrev_i32_e32 v3, 31, v2
	v_lshlrev_b64 v[10:11], 3, v[2:3]
	v_or_b32_e32 v5, v10, v5
	v_mov_b64_e32 v[2:3], s[22:23]
	v_mad_u64_u32 v[2:3], s[4:5], v5, s29, v[2:3]
	v_mad_i32_i24 v3, v11, s29, v3
	s_waitcnt lgkmcnt(0)
	v_mul_f32_e32 v5, v12, v8
	v_fmac_f32_e32 v5, v7, v9
	v_lshl_add_u64 v[10:11], v[2:3], 0, v[168:169]
	global_store_dword v[10:11], v5, off offset:16 sc1
	s_and_saveexec_b64 s[4:5], vcc
	s_cbranch_execz .LBB0_455
	ds_read_b32 v1, v1 offset:4
	ds_read_b32 v5, v6 offset:4
	s_waitcnt lgkmcnt(1)
	v_mul_f32_e32 v1, v8, v1
	s_waitcnt lgkmcnt(0)
	v_fmac_f32_e32 v1, v7, v5
	global_store_dwordx2 v[2:3], v[0:1], off sc1
.LBB0_455:
	s_or_b64 exec, exec, s[4:5]
	v_add_u32_e32 v0, 28, v4
	v_and_b32_e32 v2, -8, v0
	v_and_b32_e32 v7, 7, v0
	v_bitop3_b32 v0, v0, 7, -8 bitop3:0xe0
	v_mul_lo_u32 v0, v0, s28
	v_add_u32_e32 v1, 0x880, v6
	v_add_u32_e32 v0, 0, v0
	ds_read_b32 v3, v6 offset:2176
	ds_read_b32 v6, v0 offset:17408
	v_add_u32_e32 v4, 0x4400, v0
	v_add_u32_e32 v0, v1, v168
	v_add_u32_e32 v5, v4, v168
	ds_read_b32 v10, v0 offset:32
	ds_read_b32 v11, v5 offset:32
	s_waitcnt lgkmcnt(2)
	v_max_f32_e32 v0, v6, v6
	v_max_f32_e32 v5, v3, v3
	v_max_f32_e32 v0, v5, v0
	v_sub_f32_e32 v3, v3, v0
	v_exp_f32_e32 v5, v3
	v_sub_f32_e32 v3, v6, v0
	v_add_u32_e32 v2, s16, v2
	v_exp_f32_e32 v6, v3
	v_ashrrev_i32_e32 v3, 31, v2
	v_lshlrev_b64 v[8:9], 3, v[2:3]
	v_or_b32_e32 v7, v8, v7
	v_mov_b64_e32 v[2:3], s[22:23]
	v_mad_u64_u32 v[2:3], s[4:5], v7, s29, v[2:3]
	v_mad_i32_i24 v3, v9, s29, v3
	s_waitcnt lgkmcnt(0)
	v_mul_f32_e32 v7, v11, v6
	v_fmac_f32_e32 v7, v5, v10
	v_lshl_add_u64 v[8:9], v[2:3], 0, v[168:169]
	global_store_dword v[8:9], v7, off offset:16 sc1
	s_and_saveexec_b64 s[4:5], vcc
	s_cbranch_execz .LBB0_414
	ds_read_b32 v4, v4 offset:4
	ds_read_b32 v7, v1 offset:4
	s_waitcnt lgkmcnt(1)
	v_mul_f32_e32 v1, v6, v4
	s_waitcnt lgkmcnt(0)
	v_fmac_f32_e32 v1, v5, v7
	global_store_dwordx2 v[2:3], v[0:1], off sc1
	s_branch .LBB0_414

.LBB0_578:
	s_or_b64 exec, exec, s[6:7]
	v_ashrrev_i32_e32 v4, 7, v188
	v_mul_lo_u32 v1, v4, s29
	v_add_u32_e32 v6, 0, v1
	v_bitop3_b32 v1, v4, 7, -8 bitop3:0xe0
	v_mul_lo_u32 v1, v1, s29
	v_add_u32_e32 v3, 0, v1
	s_waitcnt lgkmcnt(0)
	s_barrier
	v_add_u32_e32 v1, 0x4400, v3
	ds_read_b32 v7, v6
	ds_read_b32 v3, v3 offset:17408
	v_and_b32_e32 v0, 0x7f, v188
	v_lshlrev_b32_e32 v168, 2, v0
	v_cmp_eq_u32_e32 vcc, 0, v0
	v_add_u32_e32 v0, v6, v168
	v_add_u32_e32 v8, v1, v168
	s_lshl_b32 s6, s43, 5
	ds_read_b32 v9, v0 offset:32
	ds_read_b32 v12, v8 offset:32
	s_waitcnt lgkmcnt(2)
	v_max_f32_e32 v0, v3, v3
	v_max_f32_e32 v8, v7, v7
	s_or_b32 s16, s6, s24
	v_and_b32_e32 v2, -8, v4
	v_max_f32_e32 v0, v8, v0
	v_sub_f32_e32 v3, v3, v0
	v_add_u32_e32 v2, s16, v2
	v_sub_f32_e32 v7, v7, v0
	v_exp_f32_e32 v8, v3
	v_ashrrev_i32_e32 v3, 31, v2
	v_and_b32_e32 v5, 7, v4
	v_exp_f32_e32 v7, v7
	v_lshlrev_b64 v[10:11], 3, v[2:3]
	v_or_b32_e32 v10, v10, v5
	v_mov_b64_e32 v[2:3], s[20:21]
	v_mad_u64_u32 v[2:3], s[6:7], v10, s30, v[2:3]
	v_mad_i32_i24 v3, v11, s30, v3
	s_waitcnt lgkmcnt(0)
	v_mul_f32_e32 v12, v12, v8
	v_fmac_f32_e32 v12, v7, v9
	v_lshl_add_u64 v[10:11], v[2:3], 0, v[168:169]
	global_store_dword v[10:11], v12, off offset:16 sc1
	s_and_saveexec_b64 s[6:7], vcc
	s_cbranch_execz .LBB0_580
	ds_read_b32 v1, v1 offset:4
	ds_read_b32 v9, v6 offset:4
	s_waitcnt lgkmcnt(1)
	v_mul_f32_e32 v1, v8, v1
	s_waitcnt lgkmcnt(0)
	v_fmac_f32_e32 v1, v7, v9
	global_store_dwordx2 v[2:3], v[0:1], off sc1
.LBB0_580:
	s_or_b64 exec, exec, s[6:7]
	v_add_u32_e32 v0, 4, v4
	v_and_b32_e32 v2, -8, v0
	v_and_b32_e32 v9, 7, v0
	v_bitop3_b32 v0, v0, 7, -8 bitop3:0xe0
	v_mul_lo_u32 v0, v0, s29
	v_add_u32_e32 v0, 0, v0
	ds_read_b32 v3, v6 offset:2176
	ds_read_b32 v8, v0 offset:17408
	v_add_u32_e32 v7, 0x880, v6
	v_add_u32_e32 v1, 0x4400, v0
	v_add_u32_e32 v0, v7, v168
	v_add_u32_e32 v6, v1, v168
	ds_read_b32 v12, v0 offset:32
	ds_read_b32 v13, v6 offset:32
	s_waitcnt lgkmcnt(2)
	v_max_f32_e32 v0, v8, v8
	v_max_f32_e32 v6, v3, v3
	v_max_f32_e32 v0, v6, v0
	v_sub_f32_e32 v3, v3, v0
	v_exp_f32_e32 v6, v3
	v_sub_f32_e32 v3, v8, v0
	v_add_u32_e32 v2, s16, v2
	v_exp_f32_e32 v8, v3
	v_ashrrev_i32_e32 v3, 31, v2
	v_lshlrev_b64 v[10:11], 3, v[2:3]
	v_or_b32_e32 v9, v10, v9
	v_mov_b64_e32 v[2:3], s[20:21]
	v_mad_u64_u32 v[2:3], s[6:7], v9, s30, v[2:3]
	v_mad_i32_i24 v3, v11, s30, v3
	s_waitcnt lgkmcnt(0)
	v_mul_f32_e32 v9, v13, v8
	v_fmac_f32_e32 v9, v6, v12
	v_lshl_add_u64 v[10:11], v[2:3], 0, v[168:169]
	global_store_dword v[10:11], v9, off offset:16 sc1
	s_and_saveexec_b64 s[6:7], vcc
	s_cbranch_execz .LBB0_582
	ds_read_b32 v1, v1 offset:4
	ds_read_b32 v9, v7 offset:4
	s_waitcnt lgkmcnt(1)
	v_mul_f32_e32 v1, v8, v1
	s_waitcnt lgkmcnt(0)
	v_fmac_f32_e32 v1, v6, v9
	global_store_dwordx2 v[2:3], v[0:1], off sc1
.LBB0_582:
	s_or_b64 exec, exec, s[6:7]
	v_add_u32_e32 v0, 8, v4
	v_and_b32_e32 v2, -8, v0
	v_or_b32_e32 v0, v2, v5
	v_mul_lo_u32 v0, v0, s29
	v_add_u32_e32 v0, 0, v0
	ds_read_b32 v3, v7 offset:2176
	ds_read_b32 v8, v0 offset:17408
	v_add_u32_e32 v6, 0x880, v7
	v_add_u32_e32 v1, 0x4400, v0
	v_add_u32_e32 v0, v6, v168
	v_add_u32_e32 v7, v1, v168
	ds_read_b32 v9, v0 offset:32
	ds_read_b32 v12, v7 offset:32
	s_waitcnt lgkmcnt(2)
	v_max_f32_e32 v0, v8, v8
	v_max_f32_e32 v7, v3, v3
	v_max_f32_e32 v0, v7, v0
	v_sub_f32_e32 v3, v3, v0
	v_exp_f32_e32 v7, v3
	v_sub_f32_e32 v3, v8, v0
	v_add_u32_e32 v2, s16, v2
	v_exp_f32_e32 v8, v3
	v_ashrrev_i32_e32 v3, 31, v2
	v_lshlrev_b64 v[10:11], 3, v[2:3]
	v_or_b32_e32 v10, v10, v5
	v_mov_b64_e32 v[2:3], s[20:21]
	v_mad_u64_u32 v[2:3], s[6:7], v10, s30, v[2:3]
	v_mad_i32_i24 v3, v11, s30, v3
	s_waitcnt lgkmcnt(0)
	v_mul_f32_e32 v12, v12, v8
	v_fmac_f32_e32 v12, v7, v9
	v_lshl_add_u64 v[10:11], v[2:3], 0, v[168:169]
	global_store_dword v[10:11], v12, off offset:16 sc1
	s_and_saveexec_b64 s[6:7], vcc
	s_cbranch_execz .LBB0_584
	ds_read_b32 v1, v1 offset:4
	ds_read_b32 v9, v6 offset:4
	s_waitcnt lgkmcnt(1)
	v_mul_f32_e32 v1, v8, v1
	s_waitcnt lgkmcnt(0)
	v_fmac_f32_e32 v1, v7, v9
	global_store_dwordx2 v[2:3], v[0:1], off sc1
.LBB0_584:
	s_or_b64 exec, exec, s[6:7]
	v_add_u32_e32 v0, 12, v4
	v_and_b32_e32 v2, -8, v0
	v_and_b32_e32 v9, 7, v0
	v_bitop3_b32 v0, v0, 7, -8 bitop3:0xe0
	v_mul_lo_u32 v0, v0, s29
	v_add_u32_e32 v0, 0, v0
	ds_read_b32 v3, v6 offset:2176
	ds_read_b32 v8, v0 offset:17408
	v_add_u32_e32 v7, 0x880, v6
	v_add_u32_e32 v1, 0x4400, v0
	v_add_u32_e32 v0, v7, v168
	v_add_u32_e32 v6, v1, v168
	ds_read_b32 v12, v0 offset:32
	ds_read_b32 v13, v6 offset:32
	s_waitcnt lgkmcnt(2)
	v_max_f32_e32 v0, v8, v8
	v_max_f32_e32 v6, v3, v3
	v_max_f32_e32 v0, v6, v0
	v_sub_f32_e32 v3, v3, v0
	v_exp_f32_e32 v6, v3
	v_sub_f32_e32 v3, v8, v0
	v_add_u32_e32 v2, s16, v2
	v_exp_f32_e32 v8, v3
	v_ashrrev_i32_e32 v3, 31, v2
	v_lshlrev_b64 v[10:11], 3, v[2:3]
	v_or_b32_e32 v9, v10, v9
	v_mov_b64_e32 v[2:3], s[20:21]
	v_mad_u64_u32 v[2:3], s[6:7], v9, s30, v[2:3]
	v_mad_i32_i24 v3, v11, s30, v3
	s_waitcnt lgkmcnt(0)
	v_mul_f32_e32 v9, v13, v8
	v_fmac_f32_e32 v9, v6, v12
	v_lshl_add_u64 v[10:11], v[2:3], 0, v[168:169]
	global_store_dword v[10:11], v9, off offset:16 sc1
	s_and_saveexec_b64 s[6:7], vcc
	s_cbranch_execz .LBB0_586
	ds_read_b32 v1, v1 offset:4
	ds_read_b32 v9, v7 offset:4
	s_waitcnt lgkmcnt(1)
	v_mul_f32_e32 v1, v8, v1
	s_waitcnt lgkmcnt(0)
	v_fmac_f32_e32 v1, v6, v9
	global_store_dwordx2 v[2:3], v[0:1], off sc1
.LBB0_586:
	s_or_b64 exec, exec, s[6:7]
	v_add_u32_e32 v0, 16, v4
	v_and_b32_e32 v2, -8, v0
	v_or_b32_e32 v0, v2, v5
	v_mul_lo_u32 v0, v0, s29
	v_add_u32_e32 v0, 0, v0
	ds_read_b32 v3, v7 offset:2176
	ds_read_b32 v8, v0 offset:17408
	v_add_u32_e32 v6, 0x880, v7
	v_add_u32_e32 v1, 0x4400, v0
	v_add_u32_e32 v0, v6, v168
	v_add_u32_e32 v7, v1, v168
	ds_read_b32 v9, v0 offset:32
	ds_read_b32 v12, v7 offset:32
	s_waitcnt lgkmcnt(2)
	v_max_f32_e32 v0, v8, v8
	v_max_f32_e32 v7, v3, v3
	v_max_f32_e32 v0, v7, v0
	v_sub_f32_e32 v3, v3, v0
	v_exp_f32_e32 v7, v3
	v_sub_f32_e32 v3, v8, v0
	v_add_u32_e32 v2, s16, v2
	v_exp_f32_e32 v8, v3
	v_ashrrev_i32_e32 v3, 31, v2
	v_lshlrev_b64 v[10:11], 3, v[2:3]
	v_or_b32_e32 v10, v10, v5
	v_mov_b64_e32 v[2:3], s[20:21]
	v_mad_u64_u32 v[2:3], s[6:7], v10, s30, v[2:3]
	v_mad_i32_i24 v3, v11, s30, v3
	s_waitcnt lgkmcnt(0)
	v_mul_f32_e32 v12, v12, v8
	v_fmac_f32_e32 v12, v7, v9
	v_lshl_add_u64 v[10:11], v[2:3], 0, v[168:169]
	global_store_dword v[10:11], v12, off offset:16 sc1
	s_and_saveexec_b64 s[6:7], vcc
	s_cbranch_execz .LBB0_588
	ds_read_b32 v1, v1 offset:4
	ds_read_b32 v9, v6 offset:4
	s_waitcnt lgkmcnt(1)
	v_mul_f32_e32 v1, v8, v1
	s_waitcnt lgkmcnt(0)
	v_fmac_f32_e32 v1, v7, v9
	global_store_dwordx2 v[2:3], v[0:1], off sc1
.LBB0_588:
	s_or_b64 exec, exec, s[6:7]
	v_add_u32_e32 v0, 20, v4
	v_and_b32_e32 v2, -8, v0
	v_and_b32_e32 v9, 7, v0
	v_bitop3_b32 v0, v0, 7, -8 bitop3:0xe0
	v_mul_lo_u32 v0, v0, s29
	v_add_u32_e32 v0, 0, v0
	ds_read_b32 v3, v6 offset:2176
	ds_read_b32 v8, v0 offset:17408
	v_add_u32_e32 v7, 0x880, v6
	v_add_u32_e32 v1, 0x4400, v0
	v_add_u32_e32 v0, v7, v168
	v_add_u32_e32 v6, v1, v168
	ds_read_b32 v12, v0 offset:32
	ds_read_b32 v13, v6 offset:32
	s_waitcnt lgkmcnt(2)
	v_max_f32_e32 v0, v8, v8
	v_max_f32_e32 v6, v3, v3
	v_max_f32_e32 v0, v6, v0
	v_sub_f32_e32 v3, v3, v0
	v_exp_f32_e32 v6, v3
	v_sub_f32_e32 v3, v8, v0
	v_add_u32_e32 v2, s16, v2
	v_exp_f32_e32 v8, v3
	v_ashrrev_i32_e32 v3, 31, v2
	v_lshlrev_b64 v[10:11], 3, v[2:3]
	v_or_b32_e32 v9, v10, v9
	v_mov_b64_e32 v[2:3], s[20:21]
	v_mad_u64_u32 v[2:3], s[6:7], v9, s30, v[2:3]
	v_mad_i32_i24 v3, v11, s30, v3
	s_waitcnt lgkmcnt(0)
	v_mul_f32_e32 v9, v13, v8
	v_fmac_f32_e32 v9, v6, v12
	v_lshl_add_u64 v[10:11], v[2:3], 0, v[168:169]
	global_store_dword v[10:11], v9, off offset:16 sc1
	s_and_saveexec_b64 s[6:7], vcc
	s_cbranch_execz .LBB0_590
	ds_read_b32 v1, v1 offset:4
	ds_read_b32 v9, v7 offset:4
	s_waitcnt lgkmcnt(1)
	v_mul_f32_e32 v1, v8, v1
	s_waitcnt lgkmcnt(0)
	v_fmac_f32_e32 v1, v6, v9
	global_store_dwordx2 v[2:3], v[0:1], off sc1
.LBB0_590:
	s_or_b64 exec, exec, s[6:7]
	v_add_u32_e32 v0, 24, v4
	v_and_b32_e32 v2, -8, v0
	v_or_b32_e32 v0, v2, v5
	v_mul_lo_u32 v0, v0, s29
	v_add_u32_e32 v0, 0, v0
	ds_read_b32 v3, v7 offset:2176
	ds_read_b32 v8, v0 offset:17408
	v_add_u32_e32 v6, 0x880, v7
	v_add_u32_e32 v1, 0x4400, v0
	v_add_u32_e32 v0, v6, v168
	v_add_u32_e32 v7, v1, v168
	ds_read_b32 v9, v0 offset:32
	ds_read_b32 v12, v7 offset:32
	s_waitcnt lgkmcnt(2)
	v_max_f32_e32 v0, v8, v8
	v_max_f32_e32 v7, v3, v3
	v_max_f32_e32 v0, v7, v0
	v_sub_f32_e32 v3, v3, v0
	v_exp_f32_e32 v7, v3
	v_sub_f32_e32 v3, v8, v0
	v_add_u32_e32 v2, s16, v2
	v_exp_f32_e32 v8, v3
	v_ashrrev_i32_e32 v3, 31, v2
	v_lshlrev_b64 v[10:11], 3, v[2:3]
	v_or_b32_e32 v5, v10, v5
	v_mov_b64_e32 v[2:3], s[20:21]
	v_mad_u64_u32 v[2:3], s[6:7], v5, s30, v[2:3]
	v_mad_i32_i24 v3, v11, s30, v3
	s_waitcnt lgkmcnt(0)
	v_mul_f32_e32 v5, v12, v8
	v_fmac_f32_e32 v5, v7, v9
	v_lshl_add_u64 v[10:11], v[2:3], 0, v[168:169]
	global_store_dword v[10:11], v5, off offset:16 sc1
	s_and_saveexec_b64 s[6:7], vcc
	s_cbranch_execz .LBB0_592
	ds_read_b32 v1, v1 offset:4
	ds_read_b32 v5, v6 offset:4
	s_waitcnt lgkmcnt(1)
	v_mul_f32_e32 v1, v8, v1
	s_waitcnt lgkmcnt(0)
	v_fmac_f32_e32 v1, v7, v5
	global_store_dwordx2 v[2:3], v[0:1], off sc1
.LBB0_592:
	s_or_b64 exec, exec, s[6:7]
	v_add_u32_e32 v0, 28, v4
	v_and_b32_e32 v2, -8, v0
	v_and_b32_e32 v7, 7, v0
	v_bitop3_b32 v0, v0, 7, -8 bitop3:0xe0
	v_mul_lo_u32 v0, v0, s29
	v_add_u32_e32 v1, 0x880, v6
	v_add_u32_e32 v0, 0, v0
	ds_read_b32 v3, v6 offset:2176
	ds_read_b32 v6, v0 offset:17408
	v_add_u32_e32 v4, 0x4400, v0
	v_add_u32_e32 v0, v1, v168
	v_add_u32_e32 v5, v4, v168
	ds_read_b32 v10, v0 offset:32
	ds_read_b32 v11, v5 offset:32
	s_waitcnt lgkmcnt(2)
	v_max_f32_e32 v0, v6, v6
	v_max_f32_e32 v5, v3, v3
	v_max_f32_e32 v0, v5, v0
	v_sub_f32_e32 v3, v3, v0
	v_exp_f32_e32 v5, v3
	v_sub_f32_e32 v3, v6, v0
	v_add_u32_e32 v2, s16, v2
	v_exp_f32_e32 v6, v3
	v_ashrrev_i32_e32 v3, 31, v2
	v_lshlrev_b64 v[8:9], 3, v[2:3]
	v_or_b32_e32 v7, v8, v7
	v_mov_b64_e32 v[2:3], s[20:21]
	v_mad_u64_u32 v[2:3], s[6:7], v7, s30, v[2:3]
	v_mad_i32_i24 v3, v9, s30, v3
	s_waitcnt lgkmcnt(0)
	v_mul_f32_e32 v7, v11, v6
	v_fmac_f32_e32 v7, v5, v10
	v_lshl_add_u64 v[8:9], v[2:3], 0, v[168:169]
	global_store_dword v[8:9], v7, off offset:16 sc1
	s_and_saveexec_b64 s[6:7], vcc
	s_cbranch_execz .LBB0_551
	ds_read_b32 v4, v4 offset:4
	ds_read_b32 v7, v1 offset:4
	s_waitcnt lgkmcnt(1)
	v_mul_f32_e32 v1, v6, v4
	s_waitcnt lgkmcnt(0)
	v_fmac_f32_e32 v1, v5, v7
	global_store_dwordx2 v[2:3], v[0:1], off sc1
	s_branch .LBB0_551
.LBB0_594:
	s_waitcnt vmcnt(0)
	v_readlane_b32 s6, v248, 5
	v_readlane_b32 s7, v248, 6
	s_and_b64 vcc, exec, s[6:7]
	s_barrier
	s_cbranch_vccz .LBB0_648
	v_mbcnt_lo_u32_b32 v0, -1, 0
	v_mbcnt_hi_u32_b32 v0, -1, v0
	s_nop 0
	v_cmp_eq_u32_e32 vcc, 0, v0
	s_and_saveexec_b64 s[6:7], vcc
	s_cbranch_execz .LBB0_647
	s_lshr_b32 s10, s92, 5
	s_lshl_b32 s10, s10, 3
	s_and_b32 s11, s92, 7
	s_lshr_b32 s16, s11, 1
	s_add_i32 s17, s10, s16
	s_sub_i32 s18, 7, s16
	s_add_i32 s18, s10, s18
	s_bfe_u32 s19, s92, 0x30002
	s_add_i32 s19, s10, s19
	s_add_i32 s10, s10, s11
	s_lshl_b32 s17, s17, 8
	s_lshl_b32 s18, s18, 8
	s_lshl_b32 s19, s19, 8
	s_lshl_b32 s10, s10, 8
	s_add_u32 s12, s0, 0x24000
	s_addc_u32 s13, s1, 0
	s_add_u32 s14, s0, 0x28700
	s_addc_u32 s15, s1, 0
	v_mov_b32_e32 v0, 0
	v_mov_b32_e32 v1, 1
	v_mov_b32_e32 v3, s17
	v_mov_b32_e32 v4, s18
	v_mov_b32_e32 v5, s19
	v_mov_b32_e32 v6, s10
	s_waitcnt vmcnt(0) lgkmcnt(0)
	global_atomic_add v3, v1, s[12:13]
	global_atomic_add v4, v1, s[12:13]
	global_atomic_add v5, v1, s[12:13]
	global_atomic_add v0, v1, s[14:15]
	s_mov_b32 s16, 0
.Lr4_wait_panel:
	global_load_dword v2, v6, s[12:13] sc1
	s_waitcnt vmcnt(0)
	v_readfirstlane_b32 s17, v2
	s_cmp_ge_u32 s17, 12
	s_cbranch_scc1 .Lr4_panel_ok
	s_sleep 1
	s_add_i32 s16, s16, 1
	s_cmp_lt_u32 s16, 0x40001
	s_cbranch_scc1 .Lr4_wait_panel
.Lr4_panel_ok:
	s_cmp_lt_u32 s2, 64
	s_cbranch_scc0 .Lr4_acq
	s_mov_b32 s16, 0

.Lr4_acq:
	buffer_inv sc1
	s_waitcnt vmcnt(0)
.LBB0_647:
	s_or_b64 exec, exec, s[6:7]
